# P2: FFN2 gate/up weight conversion moved from the post-GEMM tail into the gate/up GEMM K-loop (each GEMM wave converts one 64x64 item per unit, register-only transpose, no LDS)
# baseline (speedup 1.0000x reference)
.LBB0_172:
	v_lshrrev_b32_e32 v15, 1, v148
	v_and_b32_e32 v15, 24, v15
	v_and_b32_e32 v14, 15, v148
	v_lshlrev_b32_e32 v16, 1, v15
	v_lshl_or_b32 v150, s1, 6, v14
	v_lshl_or_b32 v14, v14, 6, v16
	v_lshlrev_b32_e32 v16, 2, v148
	s_sext_i32_i16 s36, s0
	s_lshl_b32 s0, s1, 13
	v_and_b32_e32 v16, 32, v16
	v_bitop3_b32 v17, v14, s0, v16 bitop3:0xde
	s_lshl_b32 s0, s4, 5
	s_mov_b64 s[4:5], 0x80
	s_and_b32 s8, s0, 0x60
	s_add_i32 m0, s29, 0x18000
	v_lshl_add_u64 v[6:7], v[6:7], 0, s[4:5]
	s_lshl_b32 s0, s8, 7
	s_waitcnt vmcnt(2)
	s_barrier
	global_load_lds_dwordx4 v[6:7], off
	v_lshl_add_u64 v[4:5], v[4:5], 0, s[4:5]
	s_add_i32 m0, s29, 0x1a000
	s_add_i32 s78, s29, 0x8000
	s_add_i32 s79, s29, 0xa000
	v_bitop3_b32 v151, s0, v14, v16 bitop3:0xf6
	global_load_lds_dwordx4 v[4:5], off
	v_lshl_add_u64 v[0:1], v[0:1], 0, s[4:5]
	s_mov_b32 m0, s78
	s_add_u32 s0, s74, 0x100080
	global_load_lds_dwordx4 v[0:1], off
	v_lshl_add_u64 v[0:1], v[2:3], 0, s[4:5]
	s_mov_b32 m0, s79
	s_addc_u32 s1, s75, 0
	global_load_lds_dwordx4 v[0:1], off
	s_add_i32 m0, s29, 0x1c000
	v_lshl_add_u64 v[0:1], s[0:1], 0, v[130:131]
	global_load_lds_dwordx4 v[0:1], off
	v_lshl_add_u64 v[0:1], s[0:1], 0, v[134:135]
	s_add_i32 m0, s29, 0x1e000
	s_cmpk_lt_u32 s6, 0x100
	global_load_lds_dwordx4 v[0:1], off
	v_lshlrev_b32_e32 v0, 16, v8
	v_and_b32_e32 v0, 0xfffe0000, v0
	v_lshl_add_u32 v0, v9, 13, v0
	v_and_b32_e32 v1, 1, v8
	v_lshl_or_b32 v0, v1, 6, v0
	v_lshl_add_u32 v136, v10, 1, v0
	v_lshlrev_b32_e32 v0, 16, v11
	v_and_b32_e32 v0, 0xfffe0000, v0
	s_waitcnt vmcnt(6)
	v_lshl_add_u32 v0, v12, 13, v0
	v_and_b32_e32 v1, 1, v11
	s_cselect_b64 s[6:7], -1, 0
	v_lshl_or_b32 v0, v1, 6, v0
	s_add_i32 s81, 0, 0x10000
	s_add_i32 s82, 0, 0x14000
	s_ashr_i32 s80, s9, 31
	v_or_b32_e32 v152, s8, v15
	v_mov_b32_e32 v137, v131
	v_lshl_add_u32 v138, v13, 1, v0
	v_mov_b32_e32 v139, v131
	v_mov_b64_e32 v[140:141], 0xb6c
	v_mov_b64_e32 v[142:143], 0xb6b
	v_add_u32_e32 v153, s81, v151
	v_add_u32_e32 v154, s82, v151
	v_add_u32_e32 v155, 0, v17
	s_movk_i32 s83, 0x5600
	s_mov_b32 s8, 0xbfb8aa3b
	v_readlane_b32 s98, v252, 15
	v_readlane_b32 s99, v252, 6
	s_and_b32 s100, s98, 15
	s_cmp_ge_u32 s100, 14
	s_cselect_b32 s101, 14, 0
	s_sub_i32 s100, s100, s101
	s_lshl_b32 s100, s100, 1
	v_writelane_b32 v255, s100, 8
	s_lshl_b32 s98, s98, 3
	s_add_i32 s98, s98, s99
	s_mov_b32 s99, 0
.Lcvs_div:
	s_cmpk_lt_u32 s98, 0x158
	s_cbranch_scc1 .Lcvs_div_done
	s_sub_i32 s98, s98, 0x158
	s_add_i32 s99, s99, 1
	s_branch .Lcvs_div
.Lcvs_div_done:
	v_writelane_b32 v255, s99, 9
	v_writelane_b32 v255, s98, 10
	v_readlane_b32 s98, v252, 0
	v_readlane_b32 s99, v252, 1
	s_nop 4
	s_add_u32 s98, s98, 0xffffff08
	s_addc_u32 s99, s99, -1
	s_load_dwordx2 s[100:101], s[98:99], 0xc0
	s_waitcnt lgkmcnt(0)
	v_writelane_b32 v255, s100, 12
	v_writelane_b32 v255, s101, 13
	s_barrier
	s_branch .LBB0_175
.Lcv_issue0:
	v_readlane_b32 s42, v255, 9
	v_readlane_b32 s43, v255, 10
	v_readlane_b32 s100, v255, 12
	v_readlane_b32 s101, v255, 13
	s_cmp_gt_u32 s42, 63
	s_cbranch_scc1 .Lcv_back
	s_mul_i32 s98, s42, 0x560000
	s_lshl_b32 s99, s43, 8
	s_add_u32 s98, s98, s99
	s_add_u32 s100, s100, s98
	s_addc_u32 s101, s101, 0
	v_lshrrev_b32_e32 v131, 4, v148
	v_and_b32_e32 v137, 15, v148
	v_mul_u32_u24_e32 v131, 0xac000, v131
	v_lshl_add_u32 v131, v137, 4, v131
	s_nop 1
	global_load_dwordx4 v[216:219], v131, s[100:101] nt
	s_add_u32 s100, s100, 0x15800
	s_addc_u32 s101, s101, 0
	global_load_dwordx4 v[220:223], v131, s[100:101] nt
	s_add_u32 s100, s100, 0x15800
	s_addc_u32 s101, s101, 0
	global_load_dwordx4 v[224:227], v131, s[100:101] nt
	s_add_u32 s100, s100, 0x15800
	s_addc_u32 s101, s101, 0
	global_load_dwordx4 v[228:231], v131, s[100:101] nt
	s_add_u32 s100, s100, 0x15800
	s_addc_u32 s101, s101, 0
	global_load_dwordx4 v[232:235], v131, s[100:101] nt
	s_add_u32 s100, s100, 0x15800
	s_addc_u32 s101, s101, 0
	global_load_dwordx4 v[236:239], v131, s[100:101] nt
	s_add_u32 s100, s100, 0x15800
	s_addc_u32 s101, s101, 0
	global_load_dwordx4 v[240:243], v131, s[100:101] nt
	s_add_u32 s100, s100, 0x15800
	s_addc_u32 s101, s101, 0
	global_load_dwordx4 v[244:247], v131, s[100:101] nt
	s_branch .Lcv_back
.Lcv_cons0:
	v_readlane_b32 s42, v255, 9
	v_readlane_b32 s43, v255, 10
	s_cmp_gt_u32 s42, 63
	s_cbranch_scc1 .Lcv_back
	s_cmpk_ge_u32 s43, 0xac
	s_cselect_b32 s98, 0xac, 0
	s_cselect_b32 s99, 0x80, 0
	s_sub_i32 s98, s43, s98
	s_lshr_b32 s100, s98, 1
	s_lshl_b32 s100, s100, 8
	s_and_b32 s98, s98, 1
	s_lshl_b32 s98, s98, 6
	s_add_i32 s100, s100, s99
	s_add_i32 s100, s100, s98
	s_lshl_b32 s100, s100, 13
	s_lshl_b32 s98, s42, 7
	s_add_u32 s100, s100, s98
	s_add_u32 s100, s100, 0x10a00000
	s_add_u32 s100, s90, s100
	s_addc_u32 s101, s91, 0
	v_and_b32_e32 v135, 15, v148
	v_lshrrev_b32_e32 v137, 4, v148
	v_lshlrev_b32_e32 v135, 15, v135
	v_lshl_add_u32 v135, v137, 4, v135
	s_waitcnt vmcnt(8)
	v_cvt_pk_bf16_f32 v248, v216, v220
	v_cvt_pk_bf16_f32 v249, v224, v228
	v_cvt_pk_bf16_f32 v250, v232, v236
	v_cvt_pk_bf16_f32 v251, v240, v244
	global_store_dwordx4 v135, v[248:251], s[100:101]
	s_add_u32 s100, s100, 0x2000
	s_addc_u32 s101, s101, 0
	s_nop 1
	v_cvt_pk_bf16_f32 v248, v217, v221
	v_cvt_pk_bf16_f32 v249, v225, v229
	v_cvt_pk_bf16_f32 v250, v233, v237
	v_cvt_pk_bf16_f32 v251, v241, v245
	global_store_dwordx4 v135, v[248:251], s[100:101]
	s_add_u32 s100, s100, 0x2000
	s_addc_u32 s101, s101, 0
	s_nop 1
	v_cvt_pk_bf16_f32 v248, v218, v222
	v_cvt_pk_bf16_f32 v249, v226, v230
	v_cvt_pk_bf16_f32 v250, v234, v238
	v_cvt_pk_bf16_f32 v251, v242, v246
	global_store_dwordx4 v135, v[248:251], s[100:101]
	s_add_u32 s100, s100, 0x2000
	s_addc_u32 s101, s101, 0
	s_nop 1
	v_cvt_pk_bf16_f32 v248, v219, v223
	v_cvt_pk_bf16_f32 v249, v227, v231
	v_cvt_pk_bf16_f32 v250, v235, v239
	v_cvt_pk_bf16_f32 v251, v243, v247
	global_store_dwordx4 v135, v[248:251], s[100:101]
	s_branch .Lcv_back
.Lcv_issue1:
	v_readlane_b32 s42, v255, 9
	v_readlane_b32 s43, v255, 10
	v_readlane_b32 s100, v255, 12
	v_readlane_b32 s101, v255, 13
	s_cmp_gt_u32 s42, 63
	s_cbranch_scc1 .Lcv_back
	s_mul_i32 s98, s42, 0x560000
	s_lshl_b32 s99, s43, 8
	s_add_u32 s98, s98, s99
	s_add_u32 s98, s98, 0x2b0000
	s_add_u32 s100, s100, s98
	s_addc_u32 s101, s101, 0
	v_lshrrev_b32_e32 v131, 4, v148
	v_and_b32_e32 v137, 15, v148
	v_mul_u32_u24_e32 v131, 0xac000, v131
	v_lshl_add_u32 v131, v137, 4, v131
	s_nop 1
	global_load_dwordx4 v[216:219], v131, s[100:101] nt
	s_add_u32 s100, s100, 0x15800
	s_addc_u32 s101, s101, 0
	global_load_dwordx4 v[220:223], v131, s[100:101] nt
	s_add_u32 s100, s100, 0x15800
	s_addc_u32 s101, s101, 0
	global_load_dwordx4 v[224:227], v131, s[100:101] nt
	s_add_u32 s100, s100, 0x15800
	s_addc_u32 s101, s101, 0
	global_load_dwordx4 v[228:231], v131, s[100:101] nt
	s_add_u32 s100, s100, 0x15800
	s_addc_u32 s101, s101, 0
	global_load_dwordx4 v[232:235], v131, s[100:101] nt
	s_add_u32 s100, s100, 0x15800
	s_addc_u32 s101, s101, 0
	global_load_dwordx4 v[236:239], v131, s[100:101] nt
	s_add_u32 s100, s100, 0x15800
	s_addc_u32 s101, s101, 0
	global_load_dwordx4 v[240:243], v131, s[100:101] nt
	s_add_u32 s100, s100, 0x15800
	s_addc_u32 s101, s101, 0
	global_load_dwordx4 v[244:247], v131, s[100:101] nt
	s_branch .Lcv_back
.Lcv_cons1:
	v_readlane_b32 s42, v255, 9
	v_readlane_b32 s43, v255, 10
	s_cmp_gt_u32 s42, 63
	s_cbranch_scc1 .Lcv_back
	s_cmpk_ge_u32 s43, 0xac
	s_cselect_b32 s98, 0xac, 0
	s_cselect_b32 s99, 0x80, 0
	s_sub_i32 s98, s43, s98
	s_lshr_b32 s100, s98, 1
	s_lshl_b32 s100, s100, 8
	s_and_b32 s98, s98, 1
	s_lshl_b32 s98, s98, 6
	s_add_i32 s100, s100, s99
	s_add_i32 s100, s100, s98
	s_lshl_b32 s100, s100, 13
	s_lshl_b32 s98, s42, 7
	s_add_u32 s100, s100, s98
	s_add_u32 s100, s100, 0x10a00000
	s_add_u32 s100, s90, s100
	s_addc_u32 s101, s91, 0
	v_and_b32_e32 v135, 15, v148
	v_lshrrev_b32_e32 v137, 4, v148
	v_lshlrev_b32_e32 v135, 15, v135
	v_lshl_add_u32 v135, v137, 4, v135
	s_waitcnt vmcnt(8)
	v_cvt_pk_bf16_f32 v248, v216, v220
	v_cvt_pk_bf16_f32 v249, v224, v228
	v_cvt_pk_bf16_f32 v250, v232, v236
	v_cvt_pk_bf16_f32 v251, v240, v244
	global_store_dwordx4 v135, v[248:251], s[100:101] offset:64
	s_add_u32 s100, s100, 0x2000
	s_addc_u32 s101, s101, 0
	s_nop 1
	v_cvt_pk_bf16_f32 v248, v217, v221
	v_cvt_pk_bf16_f32 v249, v225, v229
	v_cvt_pk_bf16_f32 v250, v233, v237
	v_cvt_pk_bf16_f32 v251, v241, v245
	global_store_dwordx4 v135, v[248:251], s[100:101] offset:64
	s_add_u32 s100, s100, 0x2000
	s_addc_u32 s101, s101, 0
	s_nop 1
	v_cvt_pk_bf16_f32 v248, v218, v222
	v_cvt_pk_bf16_f32 v249, v226, v230
	v_cvt_pk_bf16_f32 v250, v234, v238
	v_cvt_pk_bf16_f32 v251, v242, v246
	global_store_dwordx4 v135, v[248:251], s[100:101] offset:64
	s_add_u32 s100, s100, 0x2000
	s_addc_u32 s101, s101, 0
	s_nop 1
	v_cvt_pk_bf16_f32 v248, v219, v223
	v_cvt_pk_bf16_f32 v249, v227, v231
	v_cvt_pk_bf16_f32 v250, v235, v239
	v_cvt_pk_bf16_f32 v251, v243, v247
	global_store_dwordx4 v135, v[248:251], s[100:101] offset:64
	s_add_i32 s42, s42, 5
	s_addk_i32 s43, 0xe8
	s_cmpk_ge_u32 s43, 0x158
	s_cselect_b32 s98, 0x158, 0
	s_cselect_b32 s99, 1, 0
	s_sub_i32 s43, s43, s98
	s_add_i32 s42, s42, s99
	v_writelane_b32 v255, s42, 9
	v_writelane_b32 v255, s43, 10
	s_branch .Lcv_back

.LBB0_182:
	v_readlane_b32 s98, v255, 8
	s_sub_i32 s98, s41, s98
	s_cmp_eq_u32 s98, 0
	s_cbranch_scc1 .Lcv_issue0
	s_cmp_eq_u32 s98, 2
	s_cbranch_scc1 .Lcv_cons0
	s_cmp_eq_u32 s98, 30
	s_cbranch_scc1 .Lcv_issue1
	s_cmp_eq_u32 s98, 32
	s_cbranch_scc1 .Lcv_cons1

.LBB0_196:
	s_or_b64 exec, exec, s[30:31]
	s_waitcnt lgkmcnt(0)
	s_waitcnt lgkmcnt(0)
	s_barrier
	ds_read_b32 v0, v142
	s_mov_b64 s[30:31], -1
	s_waitcnt lgkmcnt(0)
	s_barrier
	v_readfirstlane_b32 s28, v0
	s_cmpk_gt_i32 s28, 0x158
	s_cbranch_scc1 .LBB0_191
	s_lshl_b32 s38, s28, 6
	v_readlane_b32 s28, v252, 6
	s_add_i32 s28, s38, s28
	s_cmpk_lt_i32 s28, 0x2b00
	s_movk_i32 s29, 0x2b00
	s_cbranch_scc1 .LBB0_205
	s_cmpk_gt_u32 s28, 0x413f
	s_cbranch_scc0 .LBB0_206
	s_cmpk_gt_u32 s28, 0x443f
	s_cbranch_scc0 .LBB0_207
	s_cmpk_gt_u32 s28, 0x463f
	s_cbranch_scc0 .LBB0_208
	v_readlane_b32 s40, v252, 54
	v_readlane_b32 s50, v253, 0
	v_readlane_b32 s51, v253, 1
	s_cmpk_gt_u32 s28, 0x563f
	s_mov_b64 s[76:77], -1
	s_mov_b64 s[72:73], s[50:51]
	v_readlane_b32 s41, v252, 55
	v_readlane_b32 s42, v252, 56
	v_readlane_b32 s43, v252, 57
	v_readlane_b32 s44, v252, 58
	v_readlane_b32 s45, v252, 59
	v_readlane_b32 s46, v252, 60
	v_readlane_b32 s47, v252, 61
	v_readlane_b32 s48, v252, 62
	v_readlane_b32 s49, v252, 63
	v_readlane_b32 s52, v253, 2
	v_readlane_b32 s53, v253, 3
	v_readlane_b32 s54, v253, 4
	v_readlane_b32 s55, v253, 5
	s_cbranch_scc0 .LBB0_203
	s_add_i32 s36, s28, 0xffffa9c0
	s_mov_b64 s[30:31], 0
	s_mov_b64 s[72:73], s[20:21]
